# SSD: B fragments and decay vectors of each M block requested up front (counted waits); output-part fragment reads pipelined
# baseline (speedup 1.0000x reference)
.Lssd_pf_done:
	s_cbranch_vccz .LBB0_208
	ds_read_b32 v80, v97
	ds_read_b128 v[60:63], v186
	ds_read_b128 v[56:59], v187
	ds_read_b128 v[52:55], v188
	ds_read_b128 v[48:51], v189
	v_mov_b32_e32 v65, 0
	s_andn2_b64 vcc, exec, s[2:3]
	v_add_u32_e32 v75, 0, v108
	v_add_u32_e32 v74, 0, v109
	v_add_u32_e32 v73, 0, v110
	v_add_u32_e32 v72, 0, v111
	v_mov_b32_e32 v67, 0
	v_mov_b32_e32 v66, 0
	s_cbranch_vccnz .LBB0_277
	ds_read_b128 v[216:219], v75 offset:32768
	ds_read_b128 v[220:223], v74 offset:32768
	ds_read_b128 v[232:235], v73 offset:32768
	ds_read_b128 v[246:249], v72 offset:32768
	ds_read_b128 v[76:79], v112
	ds_read_b128 v[82:85], v113
	v_readlane_b32 s34, v254, 51
	v_readlane_b32 s35, v254, 52
	s_waitcnt lgkmcnt(5)
	v_mfma_f32_16x16x32_bf16 v[66:69], v[216:219], v[60:63], 0
	s_waitcnt lgkmcnt(4)
	v_mfma_f32_16x16x32_bf16 v[66:69], v[220:223], v[56:59], v[66:69]
	s_waitcnt lgkmcnt(3)
	v_mfma_f32_16x16x32_bf16 v[66:69], v[232:235], v[52:55], v[66:69]
	s_waitcnt lgkmcnt(2)
	v_mfma_f32_16x16x32_bf16 v[66:69], v[246:249], v[48:51], v[66:69]
	s_waitcnt lgkmcnt(1)
	v_sub_f32_e32 v64, v80, v76
	v_mul_f32_e32 v64, 0x3fb8aa3b, v64
	v_exp_f32_e32 v64, v64
	s_nop 1
	v_mul_f32_e32 v64, v66, v64
	v_sub_f32_e32 v66, v80, v77
	v_mul_f32_e32 v66, 0x3fb8aa3b, v66
	v_exp_f32_e32 v66, v66
	s_waitcnt lgkmcnt(0)
	v_mul_f32_e32 v64, v82, v64
	v_cndmask_b32_e64 v64, v64, 0, s[34:35]
	v_readlane_b32 s34, v254, 47
	v_mul_f32_e32 v66, v67, v66
	v_mul_f32_e32 v66, v83, v66
	v_readlane_b32 s35, v254, 48
	v_sub_f32_e32 v67, v80, v79
	v_mul_f32_e32 v67, 0x3fb8aa3b, v67
	v_cndmask_b32_e64 v70, 0, v66, s[34:35]
	v_sub_f32_e32 v66, v80, v78
	v_mul_f32_e32 v66, 0x3fb8aa3b, v66
	v_exp_f32_e32 v66, v66
	v_exp_f32_e32 v67, v67
	v_readlane_b32 s34, v254, 45
	v_readlane_b32 s35, v254, 46
	v_pk_mul_f32 v[66:67], v[68:69], v[66:67]
	s_nop 0
	v_pk_mul_f32 v[68:69], v[84:85], v[66:67]
	v_cvt_pk_bf16_f32 v66, v64, v70
	v_cvt_pk_bf16_f32 v64, v68, v69
	v_cndmask_b32_e64 v67, v64, 0, s[34:35]
	v_readlane_b32 s34, v254, 43
	v_lshrrev_b32_e32 v64, 16, v64
	v_readlane_b32 s35, v254, 44
	s_nop 1
	v_cndmask_b32_e64 v64, v64, 0, s[34:35]
	s_mov_b32 s34, 0x5040100
	v_perm_b32 v67, v64, v67, s34
.LBB0_277:
	s_andn2_b64 vcc, exec, s[12:13]
	v_mov_b32_e32 v64, 0
	s_cbranch_vccnz .LBB0_279
	ds_read_b128 v[216:219], v75 offset:36864
	ds_read_b128 v[220:223], v74 offset:36864
	ds_read_b128 v[232:235], v73 offset:36864
	ds_read_b128 v[246:249], v72 offset:36864
	ds_read_b128 v[76:79], v118
	ds_read_b128 v[82:85], v119
	v_readlane_b32 s34, v254, 49
	v_readlane_b32 s35, v254, 50
	s_waitcnt lgkmcnt(5)
	v_mfma_f32_16x16x32_bf16 v[68:71], v[216:219], v[60:63], 0
	s_waitcnt lgkmcnt(4)
	v_mfma_f32_16x16x32_bf16 v[68:71], v[220:223], v[56:59], v[68:71]
	s_waitcnt lgkmcnt(3)
	v_mfma_f32_16x16x32_bf16 v[68:71], v[232:235], v[52:55], v[68:71]
	s_waitcnt lgkmcnt(2)
	v_mfma_f32_16x16x32_bf16 v[68:71], v[246:249], v[48:51], v[68:71]
	s_waitcnt lgkmcnt(1)
	v_sub_f32_e32 v64, v80, v76
	v_mul_f32_e32 v64, 0x3fb8aa3b, v64
	v_exp_f32_e32 v64, v64
	v_sub_f32_e32 v65, v80, v79
	v_mul_f32_e32 v65, 0x3fb8aa3b, v65
	v_exp_f32_e32 v65, v65
	v_mul_f32_e32 v64, v68, v64
	s_waitcnt lgkmcnt(0)
	v_mul_f32_e32 v64, v82, v64
	v_cndmask_b32_e64 v76, v64, 0, s[34:35]
	v_sub_f32_e32 v64, v80, v77
	v_mul_f32_e32 v64, 0x3fb8aa3b, v64
	v_exp_f32_e32 v64, v64
	v_readlane_b32 s34, v255, 4
	v_readlane_b32 s35, v255, 5
	v_mul_f32_e32 v64, v69, v64
	v_mul_f32_e32 v64, v83, v64
	v_cndmask_b32_e64 v77, 0, v64, s[34:35]
	v_sub_f32_e32 v64, v80, v78
	v_mul_f32_e32 v64, 0x3fb8aa3b, v64
	v_exp_f32_e32 v64, v64
	v_readlane_b32 s34, v255, 8
	v_readlane_b32 s35, v255, 9
	v_pk_mul_f32 v[64:65], v[70:71], v[64:65]
	s_nop 0
	v_pk_mul_f32 v[68:69], v[84:85], v[64:65]
	v_cvt_pk_bf16_f32 v64, v76, v77
	v_cvt_pk_bf16_f32 v65, v68, v69
	v_cndmask_b32_e64 v68, v65, 0, s[34:35]
	v_readlane_b32 s34, v255, 6
	v_lshrrev_b32_e32 v65, 16, v65
	v_readlane_b32 s35, v255, 7
	s_nop 1
	v_cndmask_b32_e64 v65, v65, 0, s[34:35]
	s_mov_b32 s34, 0x5040100
	v_perm_b32 v65, v65, v68, s34
.LBB0_279:
	v_mov_b32_e32 v69, 0
	s_andn2_b64 vcc, exec, s[40:41]
	v_mov_b32_e32 v71, 0
	v_mov_b32_e32 v70, 0
	s_cbranch_vccnz .LBB0_281
	ds_read_b128 v[216:219], v75 offset:40960
	ds_read_b128 v[220:223], v74 offset:40960
	ds_read_b128 v[232:235], v73 offset:40960
	ds_read_b128 v[246:249], v72 offset:40960
	ds_read_b128 v[82:85], v124
	ds_read_b128 v[202:205], v125
	v_readlane_b32 s34, v255, 10
	v_readlane_b32 s35, v255, 11
	s_waitcnt lgkmcnt(5)
	v_mfma_f32_16x16x32_bf16 v[76:79], v[216:219], v[60:63], 0
	s_waitcnt lgkmcnt(4)
	v_mfma_f32_16x16x32_bf16 v[76:79], v[220:223], v[56:59], v[76:79]
	s_waitcnt lgkmcnt(3)
	v_mfma_f32_16x16x32_bf16 v[76:79], v[232:235], v[52:55], v[76:79]
	s_waitcnt lgkmcnt(2)
	v_mfma_f32_16x16x32_bf16 v[76:79], v[246:249], v[48:51], v[76:79]
	s_waitcnt lgkmcnt(1)
	v_sub_f32_e32 v68, v80, v82
	v_mul_f32_e32 v68, 0x3fb8aa3b, v68
	v_exp_f32_e32 v68, v68
	v_sub_f32_e32 v70, v80, v83
	v_mul_f32_e32 v70, 0x3fb8aa3b, v70
	v_exp_f32_e32 v70, v70
	v_mul_f32_e32 v68, v76, v68
	s_waitcnt lgkmcnt(0)
	v_mul_f32_e32 v68, v202, v68
	v_cndmask_b32_e64 v68, v68, 0, s[34:35]
	v_mul_f32_e32 v70, v77, v70
	v_readlane_b32 s34, v254, 53
	v_mul_f32_e32 v70, v203, v70
	v_readlane_b32 s35, v254, 54
	v_sub_f32_e32 v71, v80, v85
	v_mul_f32_e32 v71, 0x3fb8aa3b, v71
	v_cndmask_b32_e64 v81, 0, v70, s[34:35]
	v_sub_f32_e32 v70, v80, v84
	v_mul_f32_e32 v70, 0x3fb8aa3b, v70
	v_exp_f32_e32 v70, v70
	v_exp_f32_e32 v71, v71
	v_readlane_b32 s34, v255, 14
	v_readlane_b32 s35, v255, 15
	v_pk_mul_f32 v[70:71], v[78:79], v[70:71]
	s_nop 0
	v_pk_mul_f32 v[76:77], v[204:205], v[70:71]
	v_cvt_pk_bf16_f32 v70, v68, v81
	v_cvt_pk_bf16_f32 v68, v76, v77
	v_cndmask_b32_e64 v71, v68, 0, s[34:35]
	v_readlane_b32 s34, v255, 12
	v_lshrrev_b32_e32 v68, 16, v68
	v_readlane_b32 s35, v255, 13
	s_nop 1
	v_cndmask_b32_e64 v68, v68, 0, s[34:35]
	s_mov_b32 s34, 0x5040100
	v_perm_b32 v71, v68, v71, s34
.LBB0_281:
	s_andn2_b64 vcc, exec, s[42:43]
	v_mov_b32_e32 v68, 0
	s_cbranch_vccnz .LBB0_283
	ds_read_b128 v[216:219], v75 offset:45056
	ds_read_b128 v[220:223], v74 offset:45056
	ds_read_b128 v[232:235], v73 offset:45056
	ds_read_b128 v[246:249], v72 offset:45056
	v_readlane_b32 s34, v255, 16
	v_readlane_b32 s35, v255, 17
	s_waitcnt lgkmcnt(3)
	v_mfma_f32_16x16x32_bf16 v[76:79], v[216:219], v[60:63], 0
	s_waitcnt lgkmcnt(2)
	v_mfma_f32_16x16x32_bf16 v[74:77], v[220:223], v[56:59], v[76:79]
	s_waitcnt lgkmcnt(1)
	v_mfma_f32_16x16x32_bf16 v[74:77], v[232:235], v[52:55], v[74:77]
	s_waitcnt lgkmcnt(0)
	v_mfma_f32_16x16x32_bf16 v[72:75], v[246:249], v[48:51], v[74:77]
	s_nop 4
	ds_read_b128 v[76:79], v130
	ds_read_b128 v[82:85], v131
	s_waitcnt lgkmcnt(1)
	v_sub_f32_e32 v68, v80, v76
	v_mul_f32_e32 v68, 0x3fb8aa3b, v68
	v_exp_f32_e32 v68, v68
	v_sub_f32_e32 v69, v80, v79
	v_mul_f32_e32 v69, 0x3fb8aa3b, v69
	v_exp_f32_e32 v69, v69
	v_mul_f32_e32 v68, v72, v68
	s_waitcnt lgkmcnt(0)
	v_mul_f32_e32 v68, v82, v68
	v_cndmask_b32_e64 v76, v68, 0, s[34:35]
	v_sub_f32_e32 v68, v80, v77
	v_mul_f32_e32 v68, 0x3fb8aa3b, v68
	v_exp_f32_e32 v68, v68
	v_readlane_b32 s34, v255, 18
	v_readlane_b32 s35, v255, 19
	v_mul_f32_e32 v68, v73, v68
	v_mul_f32_e32 v68, v83, v68
	v_cndmask_b32_e64 v77, 0, v68, s[34:35]
	v_sub_f32_e32 v68, v80, v78
	v_mul_f32_e32 v68, 0x3fb8aa3b, v68
	v_exp_f32_e32 v68, v68
	v_readlane_b32 s34, v255, 28
	v_readlane_b32 s35, v255, 29
	v_pk_mul_f32 v[68:69], v[74:75], v[68:69]
	s_nop 0
	v_pk_mul_f32 v[72:73], v[84:85], v[68:69]
	v_cvt_pk_bf16_f32 v68, v76, v77
	v_cvt_pk_bf16_f32 v69, v72, v73
	v_cndmask_b32_e64 v72, v69, 0, s[34:35]
	v_readlane_b32 s34, v255, 20
	v_lshrrev_b32_e32 v69, 16, v69
	v_readlane_b32 s35, v255, 21
	s_nop 1
	v_cndmask_b32_e64 v69, v69, 0, s[34:35]
	s_mov_b32 s34, 0x5040100
	v_perm_b32 v69, v69, v72, s34
.LBB0_283:
	v_mov_b32_e32 v73, 0
	s_andn2_b64 vcc, exec, s[46:47]
	v_mov_b32_e32 v75, 0
	v_mov_b32_e32 v74, 0
	s_cbranch_vccnz .LBB0_293
	ds_read_b128 v[216:219], v190 offset:49152
	ds_read_b128 v[220:223], v191 offset:49152
	ds_read_b128 v[232:235], v196 offset:49152
	ds_read_b128 v[246:249], v197 offset:49152
	ds_read_b128 v[82:85], v132
	ds_read_b128 v[202:205], v133
	v_readlane_b32 s34, v255, 30
	v_readlane_b32 s35, v255, 31
	s_waitcnt lgkmcnt(5)
	v_mfma_f32_16x16x32_bf16 v[74:77], v[216:219], v[60:63], 0
	s_waitcnt lgkmcnt(4)
	v_mfma_f32_16x16x32_bf16 v[74:77], v[220:223], v[56:59], v[74:77]
	s_waitcnt lgkmcnt(3)
	v_mfma_f32_16x16x32_bf16 v[74:77], v[232:235], v[52:55], v[74:77]
	s_waitcnt lgkmcnt(2)
	v_mfma_f32_16x16x32_bf16 v[74:77], v[246:249], v[48:51], v[74:77]
	s_waitcnt lgkmcnt(1)
	v_sub_f32_e32 v72, v80, v82
	v_mul_f32_e32 v72, 0x3fb8aa3b, v72
	v_exp_f32_e32 v72, v72
	s_nop 1
	v_mul_f32_e32 v72, v74, v72
	v_sub_f32_e32 v74, v80, v83
	v_mul_f32_e32 v74, 0x3fb8aa3b, v74
	v_exp_f32_e32 v74, v74
	s_waitcnt lgkmcnt(0)
	v_mul_f32_e32 v72, v202, v72
	v_cndmask_b32_e64 v72, v72, 0, s[34:35]
	v_readlane_b32 s34, v255, 32
	v_mul_f32_e32 v74, v75, v74
	v_mul_f32_e32 v74, v203, v74
	v_readlane_b32 s35, v255, 33
	v_sub_f32_e32 v75, v80, v85
	v_mul_f32_e32 v75, 0x3fb8aa3b, v75
	v_cndmask_b32_e64 v78, 0, v74, s[34:35]
	v_sub_f32_e32 v74, v80, v84
	v_mul_f32_e32 v74, 0x3fb8aa3b, v74
	v_exp_f32_e32 v74, v74
	v_exp_f32_e32 v75, v75
	v_readlane_b32 s34, v255, 36
	v_readlane_b32 s35, v255, 37
	v_pk_mul_f32 v[74:75], v[76:77], v[74:75]
	s_nop 0
	v_pk_mul_f32 v[76:77], v[204:205], v[74:75]
	v_cvt_pk_bf16_f32 v74, v72, v78
	v_cvt_pk_bf16_f32 v72, v76, v77
	v_cndmask_b32_e64 v75, v72, 0, s[78:79]
	v_lshrrev_b32_e32 v72, 16, v72
	v_cndmask_b32_e64 v72, v72, 0, s[34:35]
	s_mov_b32 s34, 0x5040100
	v_perm_b32 v75, v72, v75, s34
	s_andn2_b64 vcc, exec, s[48:49]
	v_mov_b32_e32 v72, 0
	s_cbranch_vccz .LBB0_294

.LBB0_286:
	ds_read_b128 v[216:219], v190 offset:57344
	ds_read_b128 v[220:223], v191 offset:57344
	ds_read_b128 v[232:235], v196 offset:57344
	ds_read_b128 v[246:249], v197 offset:57344
	ds_read_b128 v[82:85], v136
	ds_read_b128 v[202:205], v137
	s_mov_b32 s34, 0x5040100
	s_waitcnt lgkmcnt(5)
	v_mfma_f32_16x16x32_bf16 v[76:79], v[216:219], v[60:63], 0
	s_waitcnt lgkmcnt(4)
	v_mfma_f32_16x16x32_bf16 v[76:79], v[220:223], v[56:59], v[76:79]
	s_waitcnt lgkmcnt(3)
	v_mfma_f32_16x16x32_bf16 v[76:79], v[232:235], v[52:55], v[76:79]
	s_waitcnt lgkmcnt(2)
	v_mfma_f32_16x16x32_bf16 v[76:79], v[246:249], v[48:51], v[76:79]
	s_waitcnt lgkmcnt(1)
	v_sub_f32_e32 v81, v80, v82
	v_mul_f32_e32 v81, 0x3fb8aa3b, v81
	v_exp_f32_e32 v81, v81
	s_nop 1
	v_mul_f32_e32 v76, v76, v81
	s_waitcnt lgkmcnt(0)
	v_mul_f32_e32 v76, v202, v76
	v_cndmask_b32_e64 v81, v76, 0, s[88:89]
	v_sub_f32_e32 v76, v80, v83
	v_mul_f32_e32 v76, 0x3fb8aa3b, v76
	v_exp_f32_e32 v76, v76
	s_nop 0
	v_mul_f32_e32 v76, v77, v76
	v_mul_f32_e32 v76, v203, v76
	v_cndmask_b32_e64 v82, 0, v76, s[90:91]
	v_sub_f32_e32 v76, v80, v84
	v_sub_f32_e32 v77, v80, v85
	v_mul_f32_e32 v76, 0x3fb8aa3b, v76
	v_mul_f32_e32 v77, 0x3fb8aa3b, v77
	v_exp_f32_e32 v76, v76
	v_exp_f32_e32 v77, v77
	s_nop 0
	v_pk_mul_f32 v[76:77], v[78:79], v[76:77]
	s_nop 0
	v_pk_mul_f32 v[78:79], v[204:205], v[76:77]
	v_cvt_pk_bf16_f32 v76, v81, v82
	v_cvt_pk_bf16_f32 v77, v78, v79
	v_cndmask_b32_e64 v78, v77, 0, s[94:95]
	v_lshrrev_b32_e32 v77, 16, v77
	v_cndmask_b32_e64 v77, v77, 0, s[92:93]
	v_perm_b32 v77, v77, v78, s34
	s_mov_b64 s[34:35], -1
	s_and_b64 vcc, exec, s[52:53]
	s_cbranch_vccnz .LBB0_296

.LBB0_289:
	s_waitcnt lgkmcnt(4)
	v_mul_f32_e32 v80, 0x3fb8aa3b, v80
	v_exp_f32_e32 v89, v80
	v_add_u32_e32 v80, s17, v108
	s_waitcnt lgkmcnt(0)
	s_barrier
	ds_write_b64 v160, v[66:67] offset:32768
	ds_write_b64 v161, v[64:65] offset:32768
	ds_write_b64 v162, v[70:71] offset:32768
	ds_write_b64 v163, v[68:69] offset:32768
	ds_write_b64 v164, v[74:75] offset:32768
	ds_write_b64 v165, v[72:73] offset:32768
	ds_write_b64 v166, v[76:77] offset:32768
	ds_write_b64 v167, v[78:79] offset:32768
	s_waitcnt lgkmcnt(0)
	s_barrier
	ds_read_b128 v[76:79], v186 offset:32768
	ds_read_b128 v[72:75], v187 offset:32768
	ds_read_b128 v[68:71], v188 offset:32768
	ds_read_b128 v[64:67], v189 offset:32768
	ds_read_b128 v[216:219], v80
	v_add_u32_e32 v90, s66, v108
	ds_read_b128 v[220:223], v90
	v_add_u32_e32 v90, s17, v109
	ds_read_b128 v[232:235], v90
	v_add_u32_e32 v90, s66, v109
	ds_read_b128 v[246:249], v90
	v_add_u32_e32 v90, s17, v110
	ds_read_b128 v[202:205], v90
	v_add_u32_e32 v90, s66, v110
	ds_read_b128 v[206:209], v90
	s_andn2_b64 vcc, exec, s[30:31]
	s_waitcnt lgkmcnt(5)
	v_mfma_f32_16x16x32_bf16 v[80:83], v[216:219], v[76:79], 0
	v_add_u32_e32 v90, s17, v111
	ds_read_b128 v[216:219], v90
	s_waitcnt lgkmcnt(5)
	v_mfma_f32_16x16x32_bf16 v[84:87], v[220:223], v[60:63], 0
	v_add_u32_e32 v90, s66, v111
	ds_read_b128 v[220:223], v90
	s_waitcnt lgkmcnt(5)
	v_mfma_f32_16x16x32_bf16 v[80:83], v[232:235], v[72:75], v[80:83]
	s_waitcnt lgkmcnt(4)
	v_mfma_f32_16x16x32_bf16 v[84:87], v[246:249], v[56:59], v[84:87]
	s_waitcnt lgkmcnt(3)
	v_mfma_f32_16x16x32_bf16 v[80:83], v[202:205], v[68:71], v[80:83]
	s_waitcnt lgkmcnt(2)
	v_mfma_f32_16x16x32_bf16 v[84:87], v[206:209], v[52:55], v[84:87]
	s_waitcnt lgkmcnt(1)
	v_mfma_f32_16x16x32_bf16 v[80:83], v[216:219], v[64:67], v[80:83]
	s_waitcnt lgkmcnt(0)
	v_mfma_f32_16x16x32_bf16 v[84:87], v[220:223], v[48:51], v[84:87]
	s_nop 7
	v_fma_f32 v80, v89, v84, v80
	v_cndmask_b32_e64 v84, 0, 1, s[30:31]
	v_cmp_ne_u32_e64 s[34:35], 1, v84
	s_cbranch_vccnz .LBB0_297
	ds_read_u16 v84, v168
	s_waitcnt lgkmcnt(0)
	v_lshlrev_b32_e32 v84, 16, v84
	s_waitcnt vmcnt(0)
	v_fmac_f32_e32 v80, v200, v84
	s_and_b64 vcc, exec, s[34:35]
	v_fma_f32 v81, v89, v85, v81
	s_cbranch_vccz .LBB0_298

.LBB0_294:
	ds_read_b128 v[216:219], v190 offset:53248
	ds_read_b128 v[220:223], v191 offset:53248
	ds_read_b128 v[232:235], v196 offset:53248
	ds_read_b128 v[246:249], v197 offset:53248
	ds_read_b128 v[82:85], v134
	ds_read_b128 v[202:205], v135
	s_mov_b32 s34, 0x5040100
	s_waitcnt lgkmcnt(5)
	v_mfma_f32_16x16x32_bf16 v[76:79], v[216:219], v[60:63], 0
	s_waitcnt lgkmcnt(4)
	v_mfma_f32_16x16x32_bf16 v[76:79], v[220:223], v[56:59], v[76:79]
	s_waitcnt lgkmcnt(3)
	v_mfma_f32_16x16x32_bf16 v[76:79], v[232:235], v[52:55], v[76:79]
	s_waitcnt lgkmcnt(2)
	v_mfma_f32_16x16x32_bf16 v[76:79], v[246:249], v[48:51], v[76:79]
	s_waitcnt lgkmcnt(1)
	v_sub_f32_e32 v72, v80, v82
	v_mul_f32_e32 v72, 0x3fb8aa3b, v72
	v_exp_f32_e32 v72, v72
	v_sub_f32_e32 v73, v80, v85
	v_mul_f32_e32 v73, 0x3fb8aa3b, v73
	v_exp_f32_e32 v73, v73
	v_mul_f32_e32 v72, v76, v72
	s_waitcnt lgkmcnt(0)
	v_mul_f32_e32 v72, v202, v72
	v_cndmask_b32_e64 v81, v72, 0, s[80:81]
	v_sub_f32_e32 v72, v80, v83
	v_mul_f32_e32 v72, 0x3fb8aa3b, v72
	v_exp_f32_e32 v72, v72
	s_nop 0
	v_mul_f32_e32 v72, v77, v72
	v_mul_f32_e32 v72, v203, v72
	v_cndmask_b32_e64 v82, 0, v72, s[82:83]
	v_sub_f32_e32 v72, v80, v84
	v_mul_f32_e32 v72, 0x3fb8aa3b, v72
	v_exp_f32_e32 v72, v72
	s_nop 0
	v_pk_mul_f32 v[72:73], v[78:79], v[72:73]
	s_nop 0
	v_pk_mul_f32 v[76:77], v[204:205], v[72:73]
	v_cvt_pk_bf16_f32 v72, v81, v82
	v_cvt_pk_bf16_f32 v73, v76, v77
	v_cndmask_b32_e64 v76, v73, 0, s[86:87]
	v_lshrrev_b32_e32 v73, 16, v73
	v_cndmask_b32_e64 v73, v73, 0, s[84:85]
	v_perm_b32 v73, v73, v76, s34
	v_mov_b32_e32 v77, 0
	s_andn2_b64 vcc, exec, s[50:51]
	v_mov_b32_e32 v76, 0
	s_cbranch_vccz .LBB0_286

.LBB0_296:
	ds_read_b128 v[216:219], v190 offset:61440
	ds_read_b128 v[220:223], v191 offset:61440
	ds_read_b128 v[232:235], v196 offset:61440
	ds_read_b128 v[246:249], v197 offset:61440
	ds_read_b128 v[202:205], v138
	ds_read_b128 v[206:209], v139
	s_mov_b32 s34, 0x5040100
	s_waitcnt lgkmcnt(5)
	v_mfma_f32_16x16x32_bf16 v[82:85], v[216:219], v[60:63], 0
	s_waitcnt lgkmcnt(4)
	v_mfma_f32_16x16x32_bf16 v[82:85], v[220:223], v[56:59], v[82:85]
	s_waitcnt lgkmcnt(3)
	v_mfma_f32_16x16x32_bf16 v[82:85], v[232:235], v[52:55], v[82:85]
	s_waitcnt lgkmcnt(2)
	v_mfma_f32_16x16x32_bf16 v[82:85], v[246:249], v[48:51], v[82:85]
	s_waitcnt lgkmcnt(1)
	v_sub_f32_e32 v78, v80, v202
	v_mul_f32_e32 v78, 0x3fb8aa3b, v78
	v_exp_f32_e32 v78, v78
	v_sub_f32_e32 v79, v80, v205
	v_mul_f32_e32 v79, 0x3fb8aa3b, v79
	v_exp_f32_e32 v79, v79
	v_mul_f32_e32 v78, v82, v78
	s_waitcnt lgkmcnt(0)
	v_mul_f32_e32 v78, v206, v78
	v_cndmask_b32_e64 v81, v78, 0, s[96:97]
	v_sub_f32_e32 v78, v80, v203
	v_mul_f32_e32 v78, 0x3fb8aa3b, v78
	v_exp_f32_e32 v78, v78
	s_nop 0
	v_mul_f32_e32 v78, v83, v78
	v_mul_f32_e32 v78, v207, v78
	v_cndmask_b32_e64 v86, 0, v78, s[4:5]
	v_sub_f32_e32 v78, v80, v204
	v_mul_f32_e32 v78, 0x3fb8aa3b, v78
	v_exp_f32_e32 v78, v78
	s_nop 0
	v_pk_mul_f32 v[78:79], v[84:85], v[78:79]
	s_nop 0
	v_pk_mul_f32 v[82:83], v[208:209], v[78:79]
	v_cvt_pk_bf16_f32 v78, v81, v86
	v_cvt_pk_bf16_f32 v79, v82, v83
	v_cndmask_b32_e64 v81, v79, 0, s[8:9]
	v_lshrrev_b32_e32 v79, 16, v79
	v_cndmask_b32_e64 v79, v79, 0, s[6:7]
	v_perm_b32 v79, v79, v81, s34
	s_cbranch_execz .LBB0_288
	s_branch .LBB0_289

.LBB0_301:
	s_add_i32 s44, s44, -2
	s_lshl_b64 s[36:37], s[44:45], 17
	v_lshl_add_u64 v[100:101], v[92:93], 0, s[36:37]
	v_cvt_pk_bf16_f32 v80, v80, v81
	v_cvt_pk_bf16_f32 v81, v82, v83
	global_store_dwordx2 v[100:101], v[80:81], off
	v_add_u32_e32 v80, s17, v114
	ds_read_b128 v[216:219], v80
	v_add_u32_e32 v90, s66, v114
	ds_read_b128 v[220:223], v90
	v_add_u32_e32 v90, s17, v115
	ds_read_b128 v[232:235], v90
	v_add_u32_e32 v90, s66, v115
	ds_read_b128 v[246:249], v90
	v_add_u32_e32 v90, s17, v116
	ds_read_b128 v[202:205], v90
	v_add_u32_e32 v90, s66, v116
	ds_read_b128 v[206:209], v90
	s_and_b64 vcc, exec, s[34:35]
	s_waitcnt lgkmcnt(5)
	v_mfma_f32_16x16x32_bf16 v[80:83], v[216:219], v[76:79], 0
	v_add_u32_e32 v90, s17, v117
	ds_read_b128 v[216:219], v90
	s_waitcnt lgkmcnt(5)
	v_mfma_f32_16x16x32_bf16 v[84:87], v[220:223], v[60:63], 0
	v_add_u32_e32 v90, s66, v117
	ds_read_b128 v[220:223], v90
	s_waitcnt lgkmcnt(5)
	v_mfma_f32_16x16x32_bf16 v[80:83], v[232:235], v[72:75], v[80:83]
	s_waitcnt lgkmcnt(4)
	v_mfma_f32_16x16x32_bf16 v[84:87], v[246:249], v[56:59], v[84:87]
	s_waitcnt lgkmcnt(3)
	v_mfma_f32_16x16x32_bf16 v[80:83], v[202:205], v[68:71], v[80:83]
	s_waitcnt lgkmcnt(2)
	v_mfma_f32_16x16x32_bf16 v[84:87], v[206:209], v[52:55], v[84:87]
	s_waitcnt lgkmcnt(1)
	v_mfma_f32_16x16x32_bf16 v[80:83], v[216:219], v[64:67], v[80:83]
	s_waitcnt lgkmcnt(0)
	v_mfma_f32_16x16x32_bf16 v[84:87], v[220:223], v[48:51], v[84:87]
	s_nop 7
	v_fma_f32 v80, v89, v84, v80
	s_cbranch_vccnz .LBB0_305
	ds_read_u16 v84, v198 offset:4096
	s_waitcnt lgkmcnt(0)
	v_lshlrev_b32_e32 v84, 16, v84
	s_waitcnt vmcnt(1)
	v_fmac_f32_e32 v80, v200, v84
	s_and_b64 vcc, exec, s[34:35]
	v_fma_f32 v81, v89, v85, v81
	s_cbranch_vccz .LBB0_306

.LBB0_309:
	v_cvt_pk_bf16_f32 v80, v80, v81
	v_cvt_pk_bf16_f32 v81, v82, v83
	global_store_dwordx2 v[100:101], v[80:81], off offset:32
	v_add_u32_e32 v80, s17, v120
	ds_read_b128 v[216:219], v80
	v_add_u32_e32 v90, s66, v120
	ds_read_b128 v[220:223], v90
	v_add_u32_e32 v90, s17, v121
	ds_read_b128 v[232:235], v90
	v_add_u32_e32 v90, s66, v121
	ds_read_b128 v[246:249], v90
	v_add_u32_e32 v90, s17, v122
	ds_read_b128 v[202:205], v90
	v_add_u32_e32 v90, s66, v122
	ds_read_b128 v[206:209], v90
	s_and_b64 vcc, exec, s[34:35]
	s_waitcnt lgkmcnt(5)
	v_mfma_f32_16x16x32_bf16 v[80:83], v[216:219], v[76:79], 0
	v_add_u32_e32 v90, s17, v123
	ds_read_b128 v[216:219], v90
	s_waitcnt lgkmcnt(5)
	v_mfma_f32_16x16x32_bf16 v[84:87], v[220:223], v[60:63], 0
	v_add_u32_e32 v90, s66, v123
	ds_read_b128 v[220:223], v90
	s_waitcnt lgkmcnt(5)
	v_mfma_f32_16x16x32_bf16 v[80:83], v[232:235], v[72:75], v[80:83]
	s_waitcnt lgkmcnt(4)
	v_mfma_f32_16x16x32_bf16 v[84:87], v[246:249], v[56:59], v[84:87]
	s_waitcnt lgkmcnt(3)
	v_mfma_f32_16x16x32_bf16 v[80:83], v[202:205], v[68:71], v[80:83]
	s_waitcnt lgkmcnt(2)
	v_mfma_f32_16x16x32_bf16 v[84:87], v[206:209], v[52:55], v[84:87]
	s_waitcnt lgkmcnt(1)
	v_mfma_f32_16x16x32_bf16 v[80:83], v[216:219], v[64:67], v[80:83]
	s_waitcnt lgkmcnt(0)
	v_mfma_f32_16x16x32_bf16 v[84:87], v[220:223], v[48:51], v[84:87]
	s_nop 7
	v_fma_f32 v80, v89, v84, v80
	s_cbranch_vccnz .LBB0_313
	ds_read_u16 v84, v198 offset:8192
	s_waitcnt lgkmcnt(0)
	v_lshlrev_b32_e32 v84, 16, v84
	s_waitcnt vmcnt(2)
	v_fmac_f32_e32 v80, v200, v84
	s_and_b64 vcc, exec, s[34:35]
	v_fma_f32 v81, v89, v85, v81
	s_cbranch_vccz .LBB0_314

.LBB0_317:
	v_cvt_pk_bf16_f32 v80, v80, v81
	v_cvt_pk_bf16_f32 v81, v82, v83
	global_store_dwordx2 v[100:101], v[80:81], off offset:64
	v_add_u32_e32 v80, s17, v126
	ds_read_b128 v[216:219], v80
	v_add_u32_e32 v90, s66, v126
	ds_read_b128 v[220:223], v90
	v_add_u32_e32 v90, s17, v127
	ds_read_b128 v[232:235], v90
	v_add_u32_e32 v90, s66, v127
	ds_read_b128 v[246:249], v90
	v_add_u32_e32 v90, s17, v128
	ds_read_b128 v[202:205], v90
	v_add_u32_e32 v90, s66, v128
	ds_read_b128 v[206:209], v90
	s_and_b64 vcc, exec, s[34:35]
	s_waitcnt lgkmcnt(5)
	v_mfma_f32_16x16x32_bf16 v[80:83], v[216:219], v[76:79], 0
	v_add_u32_e32 v90, s17, v129
	ds_read_b128 v[216:219], v90
	s_waitcnt lgkmcnt(5)
	v_mfma_f32_16x16x32_bf16 v[84:87], v[220:223], v[60:63], 0
	v_add_u32_e32 v90, s66, v129
	ds_read_b128 v[220:223], v90
	s_waitcnt lgkmcnt(5)
	v_mfma_f32_16x16x32_bf16 v[80:83], v[232:235], v[72:75], v[80:83]
	s_waitcnt lgkmcnt(4)
	v_mfma_f32_16x16x32_bf16 v[84:87], v[246:249], v[56:59], v[84:87]
	s_waitcnt lgkmcnt(3)
	v_mfma_f32_16x16x32_bf16 v[80:83], v[202:205], v[68:71], v[80:83]
	s_waitcnt lgkmcnt(2)
	v_mfma_f32_16x16x32_bf16 v[84:87], v[206:209], v[52:55], v[84:87]
	s_waitcnt lgkmcnt(1)
	v_mfma_f32_16x16x32_bf16 v[80:83], v[216:219], v[64:67], v[80:83]
	s_waitcnt lgkmcnt(0)
	v_mfma_f32_16x16x32_bf16 v[84:87], v[220:223], v[48:51], v[84:87]
	s_nop 7
	v_mov_b32_e32 v52, v80
	v_mov_b32_e32 v53, v81
	v_mov_b32_e32 v54, v82
	v_mov_b32_e32 v55, v83
	v_mov_b32_e32 v48, v84
	v_mov_b32_e32 v49, v85
	v_mov_b32_e32 v50, v86
	v_mov_b32_e32 v51, v87
	s_nop 7
	v_fma_f32 v48, v89, v48, v52
	s_cbranch_vccnz .LBB0_321
	ds_read_u16 v52, v198 offset:12288
	s_waitcnt lgkmcnt(0)
	v_lshlrev_b32_e32 v52, 16, v52
	s_waitcnt vmcnt(3)
	v_fmac_f32_e32 v48, v200, v52
	s_and_b64 vcc, exec, s[34:35]
	v_fma_f32 v49, v89, v49, v53
	s_cbranch_vccz .LBB0_322

.LBB0_332:
	s_or_b64 exec, exec, s[6:7]
	s_waitcnt lgkmcnt(0)
	s_lshl_b64 s[4:5], s[14:15], 11
	v_ashrrev_i32_e32 v64, 5, v177
	v_lshl_add_u32 v67, v64, 4, v179
	ds_read2_b32 v[70:71], v67 offset1:1
	ds_read2_b32 v[72:73], v67 offset0:2 offset1:3
	ds_read2_b32 v[74:75], v67 offset0:8 offset1:9
	ds_read2_b32 v[76:77], v67 offset0:10 offset1:11
	ds_read2_b32 v[78:79], v67 offset0:16 offset1:17
	ds_read2_b32 v[80:81], v67 offset0:18 offset1:19
	ds_read2_b32 v[82:83], v67 offset0:24 offset1:25
	ds_read2_b32 v[84:85], v67 offset0:26 offset1:27
	s_add_u32 s4, s10, s4
	s_addc_u32 s5, s11, s5
	s_add_u32 s4, s4, s18
	s_addc_u32 s5, s5, s19
	s_add_i32 s31, s31, 1
	v_readlane_b32 s6, v254, 41
	v_readlane_b32 s7, v254, 42
	v_and_b32_e32 v65, 31, v177
	v_lshlrev_b32_e32 v66, 8, v178
	v_lshl_add_u32 v66, v64, 10, v66
	v_lshl_add_u32 v66, v65, 1, v66
	v_add_u32_e32 v66, 0x11000, v66
	s_waitcnt lgkmcnt(0)
	v_rcp_f32_e32 v70, v70
	v_rcp_f32_e32 v71, v71
	v_rcp_f32_e32 v72, v72
	v_rcp_f32_e32 v73, v73
	v_rcp_f32_e32 v74, v74
	v_rcp_f32_e32 v75, v75
	v_rcp_f32_e32 v76, v76
	v_rcp_f32_e32 v77, v77
	v_rcp_f32_e32 v78, v78
	v_rcp_f32_e32 v79, v79
	v_rcp_f32_e32 v80, v80
	v_rcp_f32_e32 v81, v81
	v_rcp_f32_e32 v82, v82
	v_rcp_f32_e32 v83, v83
	v_rcp_f32_e32 v84, v84
	v_rcp_f32_e32 v85, v85
	s_nop 1
	v_mul_f32_e32 v0, v0, v70
	v_cvt_pk_bf16_f32 v0, v0, v193
	ds_write_b16 v66, v0 offset:0
	v_mul_f32_e32 v48, v48, v70
	v_cvt_pk_bf16_f32 v48, v48, v193
	ds_write_b16 v66, v48 offset:64
	v_mul_f32_e32 v32, v32, v70
	v_cvt_pk_bf16_f32 v32, v32, v193
	ds_write_b16 v66, v32 offset:128
	v_mul_f32_e32 v16, v16, v70
	v_cvt_pk_bf16_f32 v16, v16, v193
	ds_write_b16 v66, v16 offset:192
	v_mul_f32_e32 v1, v1, v71
	v_cvt_pk_bf16_f32 v1, v1, v193
	ds_write_b16 v66, v1 offset:256
	v_mul_f32_e32 v49, v49, v71
	v_cvt_pk_bf16_f32 v49, v49, v193
	ds_write_b16 v66, v49 offset:320
	v_mul_f32_e32 v33, v33, v71
	v_cvt_pk_bf16_f32 v33, v33, v193
	ds_write_b16 v66, v33 offset:384
	v_mul_f32_e32 v17, v17, v71
	v_cvt_pk_bf16_f32 v17, v17, v193
	ds_write_b16 v66, v17 offset:448
	s_waitcnt lgkmcnt(7)
	v_mul_f32_e32 v2, v2, v72
	v_cvt_pk_bf16_f32 v2, v2, v193
	ds_write_b16 v66, v2 offset:512
	v_mul_f32_e32 v50, v50, v72
	v_cvt_pk_bf16_f32 v50, v50, v193
	ds_write_b16 v66, v50 offset:576
	v_mul_f32_e32 v34, v34, v72
	v_cvt_pk_bf16_f32 v34, v34, v193
	ds_write_b16 v66, v34 offset:640
	v_mul_f32_e32 v18, v18, v72
	v_cvt_pk_bf16_f32 v18, v18, v193
	ds_write_b16 v66, v18 offset:704
	v_mul_f32_e32 v3, v3, v73
	v_cvt_pk_bf16_f32 v3, v3, v193
	ds_write_b16 v66, v3 offset:768
	v_mul_f32_e32 v51, v51, v73
	v_cvt_pk_bf16_f32 v51, v51, v193
	ds_write_b16 v66, v51 offset:832
	v_mul_f32_e32 v35, v35, v73
	v_cvt_pk_bf16_f32 v35, v35, v193
	ds_write_b16 v66, v35 offset:896
	v_mul_f32_e32 v19, v19, v73
	v_cvt_pk_bf16_f32 v19, v19, v193
	ds_write_b16 v66, v19 offset:960
	s_waitcnt lgkmcnt(7)
	v_mul_f32_e32 v4, v4, v74
	v_cvt_pk_bf16_f32 v4, v4, v193
	ds_write_b16 v66, v4 offset:2048
	v_mul_f32_e32 v52, v52, v74
	v_cvt_pk_bf16_f32 v52, v52, v193
	ds_write_b16 v66, v52 offset:2112
	v_mul_f32_e32 v36, v36, v74
	v_cvt_pk_bf16_f32 v36, v36, v193
	ds_write_b16 v66, v36 offset:2176
	v_mul_f32_e32 v20, v20, v74
	v_cvt_pk_bf16_f32 v20, v20, v193
	ds_write_b16 v66, v20 offset:2240
	v_mul_f32_e32 v5, v5, v75
	v_cvt_pk_bf16_f32 v5, v5, v193
	ds_write_b16 v66, v5 offset:2304
	v_mul_f32_e32 v53, v53, v75
	v_cvt_pk_bf16_f32 v53, v53, v193
	ds_write_b16 v66, v53 offset:2368
	v_mul_f32_e32 v37, v37, v75
	v_cvt_pk_bf16_f32 v37, v37, v193
	ds_write_b16 v66, v37 offset:2432
	v_mul_f32_e32 v21, v21, v75
	v_cvt_pk_bf16_f32 v21, v21, v193
	ds_write_b16 v66, v21 offset:2496
	s_waitcnt lgkmcnt(7)
	v_mul_f32_e32 v6, v6, v76
	v_cvt_pk_bf16_f32 v6, v6, v193
	ds_write_b16 v66, v6 offset:2560
	v_mul_f32_e32 v54, v54, v76
	v_cvt_pk_bf16_f32 v54, v54, v193
	ds_write_b16 v66, v54 offset:2624
	v_mul_f32_e32 v38, v38, v76
	v_cvt_pk_bf16_f32 v38, v38, v193
	ds_write_b16 v66, v38 offset:2688
	v_mul_f32_e32 v22, v22, v76
	v_cvt_pk_bf16_f32 v22, v22, v193
	ds_write_b16 v66, v22 offset:2752
	v_mul_f32_e32 v7, v7, v77
	v_cvt_pk_bf16_f32 v7, v7, v193
	ds_write_b16 v66, v7 offset:2816
	v_mul_f32_e32 v55, v55, v77
	v_cvt_pk_bf16_f32 v55, v55, v193
	ds_write_b16 v66, v55 offset:2880
	v_mul_f32_e32 v39, v39, v77
	v_cvt_pk_bf16_f32 v39, v39, v193
	ds_write_b16 v66, v39 offset:2944
	v_mul_f32_e32 v23, v23, v77
	v_cvt_pk_bf16_f32 v23, v23, v193
	ds_write_b16 v66, v23 offset:3008
	s_waitcnt lgkmcnt(7)
	v_mul_f32_e32 v8, v8, v78
	v_cvt_pk_bf16_f32 v8, v8, v193
	ds_write_b16 v66, v8 offset:4096
	v_mul_f32_e32 v56, v56, v78
	v_cvt_pk_bf16_f32 v56, v56, v193
	ds_write_b16 v66, v56 offset:4160
	v_mul_f32_e32 v40, v40, v78
	v_cvt_pk_bf16_f32 v40, v40, v193
	ds_write_b16 v66, v40 offset:4224
	v_mul_f32_e32 v24, v24, v78
	v_cvt_pk_bf16_f32 v24, v24, v193
	ds_write_b16 v66, v24 offset:4288
	v_mul_f32_e32 v9, v9, v79
	v_cvt_pk_bf16_f32 v9, v9, v193
	ds_write_b16 v66, v9 offset:4352
	v_mul_f32_e32 v57, v57, v79
	v_cvt_pk_bf16_f32 v57, v57, v193
	ds_write_b16 v66, v57 offset:4416
	v_mul_f32_e32 v41, v41, v79
	v_cvt_pk_bf16_f32 v41, v41, v193
	ds_write_b16 v66, v41 offset:4480
	v_mul_f32_e32 v25, v25, v79
	v_cvt_pk_bf16_f32 v25, v25, v193
	ds_write_b16 v66, v25 offset:4544
	s_waitcnt lgkmcnt(7)
	v_mul_f32_e32 v10, v10, v80
	v_cvt_pk_bf16_f32 v10, v10, v193
	ds_write_b16 v66, v10 offset:4608
	v_mul_f32_e32 v58, v58, v80
	v_cvt_pk_bf16_f32 v58, v58, v193
	ds_write_b16 v66, v58 offset:4672
	v_mul_f32_e32 v42, v42, v80
	v_cvt_pk_bf16_f32 v42, v42, v193
	ds_write_b16 v66, v42 offset:4736
	v_mul_f32_e32 v26, v26, v80
	v_cvt_pk_bf16_f32 v26, v26, v193
	ds_write_b16 v66, v26 offset:4800
	v_mul_f32_e32 v11, v11, v81
	v_cvt_pk_bf16_f32 v11, v11, v193
	ds_write_b16 v66, v11 offset:4864
	v_mul_f32_e32 v59, v59, v81
	v_cvt_pk_bf16_f32 v59, v59, v193
	ds_write_b16 v66, v59 offset:4928
	v_mul_f32_e32 v43, v43, v81
	v_cvt_pk_bf16_f32 v43, v43, v193
	ds_write_b16 v66, v43 offset:4992
	v_mul_f32_e32 v27, v27, v81
	v_cvt_pk_bf16_f32 v27, v27, v193
	ds_write_b16 v66, v27 offset:5056
	s_waitcnt lgkmcnt(7)
	v_mul_f32_e32 v12, v12, v82
	v_cvt_pk_bf16_f32 v12, v12, v193
	ds_write_b16 v66, v12 offset:6144
	v_mul_f32_e32 v60, v60, v82
	v_cvt_pk_bf16_f32 v60, v60, v193
	ds_write_b16 v66, v60 offset:6208
	v_mul_f32_e32 v44, v44, v82
	v_cvt_pk_bf16_f32 v44, v44, v193
	ds_write_b16 v66, v44 offset:6272
	v_mul_f32_e32 v28, v28, v82
	v_cvt_pk_bf16_f32 v28, v28, v193
	ds_write_b16 v66, v28 offset:6336
	v_mul_f32_e32 v13, v13, v83
	v_cvt_pk_bf16_f32 v13, v13, v193
	ds_write_b16 v66, v13 offset:6400
	v_mul_f32_e32 v61, v61, v83
	v_cvt_pk_bf16_f32 v61, v61, v193
	ds_write_b16 v66, v61 offset:6464
	v_mul_f32_e32 v45, v45, v83
	v_cvt_pk_bf16_f32 v45, v45, v193
	ds_write_b16 v66, v45 offset:6528
	v_mul_f32_e32 v29, v29, v83
	v_cvt_pk_bf16_f32 v29, v29, v193
	ds_write_b16 v66, v29 offset:6592
	s_waitcnt lgkmcnt(7)
	v_mul_f32_e32 v14, v14, v84
	v_cvt_pk_bf16_f32 v14, v14, v193
	ds_write_b16 v66, v14 offset:6656
	v_mul_f32_e32 v62, v62, v84
	v_cvt_pk_bf16_f32 v62, v62, v193
	ds_write_b16 v66, v62 offset:6720
	v_mul_f32_e32 v46, v46, v84
	v_cvt_pk_bf16_f32 v46, v46, v193
	ds_write_b16 v66, v46 offset:6784
	v_mul_f32_e32 v30, v30, v84
	v_cvt_pk_bf16_f32 v30, v30, v193
	ds_write_b16 v66, v30 offset:6848
	v_mul_f32_e32 v15, v15, v85
	v_cvt_pk_bf16_f32 v15, v15, v193
	ds_write_b16 v66, v15 offset:6912
	v_mul_f32_e32 v63, v63, v85
	v_cvt_pk_bf16_f32 v63, v63, v193
	ds_write_b16 v66, v63 offset:6976
	v_mul_f32_e32 v47, v47, v85
	v_cvt_pk_bf16_f32 v47, v47, v193
	ds_write_b16 v66, v47 offset:7040
	v_mul_f32_e32 v31, v31, v85
	v_cvt_pk_bf16_f32 v31, v31, v193
	ds_write_b16 v66, v31 offset:7104
	v_lshrrev_b32_e32 v64, 4, v177
	v_and_b32_e32 v65, 15, v177
	v_lshlrev_b32_e32 v66, 8, v178
	v_lshl_add_u32 v66, v64, 8, v66
	v_lshl_add_u32 v66, v65, 4, v66
	v_add_u32_e32 v66, 0x11000, v66
	v_add_u32_e32 v68, v178, v64
	v_mov_b32_e32 v69, 0
	v_lshlrev_b64 v[68:69], 11, v[68:69]
	v_lshl_add_u64 v[68:69], s[4:5], 0, v[68:69]
	v_lshlrev_b32_e32 v70, 4, v65
	v_mov_b32_e32 v71, 0
	v_lshl_add_u64 v[68:69], v[68:69], 0, v[70:71]
	s_waitcnt lgkmcnt(0)
	ds_read_b128 v[0:3], v66 offset:0
	ds_read_b128 v[4:7], v66 offset:1024
	ds_read_b128 v[8:11], v66 offset:2048
	ds_read_b128 v[12:15], v66 offset:3072
	ds_read_b128 v[16:19], v66 offset:4096
	ds_read_b128 v[20:23], v66 offset:5120
	ds_read_b128 v[24:27], v66 offset:6144
	ds_read_b128 v[28:31], v66 offset:7168
	s_waitcnt lgkmcnt(7)
	global_store_dwordx4 v[68:69], v[0:3], off offset:1024
	v_add_co_u32_e32 v68, vcc, 0x2000, v68
	s_nop 1
	v_addc_co_u32_e32 v69, vcc, 0, v69, vcc
	s_waitcnt lgkmcnt(6)
	global_store_dwordx4 v[68:69], v[4:7], off offset:1024
	v_add_co_u32_e32 v68, vcc, 0x2000, v68
	s_nop 1
	v_addc_co_u32_e32 v69, vcc, 0, v69, vcc
	s_waitcnt lgkmcnt(5)
	global_store_dwordx4 v[68:69], v[8:11], off offset:1024
	v_add_co_u32_e32 v68, vcc, 0x2000, v68
	s_nop 1
	v_addc_co_u32_e32 v69, vcc, 0, v69, vcc
	s_waitcnt lgkmcnt(4)
	global_store_dwordx4 v[68:69], v[12:15], off offset:1024
	v_add_co_u32_e32 v68, vcc, 0x2000, v68
	s_nop 1
	v_addc_co_u32_e32 v69, vcc, 0, v69, vcc
	s_waitcnt lgkmcnt(3)
	global_store_dwordx4 v[68:69], v[16:19], off offset:1024
	v_add_co_u32_e32 v68, vcc, 0x2000, v68
	s_nop 1
	v_addc_co_u32_e32 v69, vcc, 0, v69, vcc
	s_waitcnt lgkmcnt(2)
	global_store_dwordx4 v[68:69], v[20:23], off offset:1024
	v_add_co_u32_e32 v68, vcc, 0x2000, v68
	s_nop 1
	v_addc_co_u32_e32 v69, vcc, 0, v69, vcc
	s_waitcnt lgkmcnt(1)
	global_store_dwordx4 v[68:69], v[24:27], off offset:1024
	v_add_co_u32_e32 v68, vcc, 0x2000, v68
	s_nop 1
	v_addc_co_u32_e32 v69, vcc, 0, v69, vcc
	s_waitcnt lgkmcnt(0)
	global_store_dwordx4 v[68:69], v[28:31], off offset:1024
	s_branch .Lattn_epi_pad_end
	s_nop 0
	s_nop 0
	s_nop 0
	s_nop 0
	s_nop 0
	s_nop 0
	s_nop 0
	s_nop 0
	s_nop 0
	s_nop 0
	s_nop 0
	s_nop 0
	s_nop 0
	s_nop 0
	s_nop 0
	s_nop 0
	s_nop 0
	s_nop 0
	s_nop 0
	s_nop 0
	s_nop 0
	s_nop 0
	s_nop 0
.Lattn_epi_pad_end:
	s_mul_i32 s4, s31, s82
	s_add_i32 s14, s4, s6
	s_cmpk_lt_i32 s14, 0x480
	s_cbranch_scc0 .LBB0_358
